# mixer preamble: all 59 rpb loads in flight under one wait (was 4 rounds of 16)
# speedup vs baseline: 1.0042x; 1.0010x over previous
.Lmx_prio_skip:
	s_add_u32 s2, s50, s7
	v_and_b32_e32 v2, 63, v0
	v_readlane_b32 s6, v255, 17
	s_addc_u32 s3, s51, s6
	v_lshlrev_b32_e32 v0, 2, v2
	v_mov_b32_e32 v1, v113
	v_lshl_add_u64 v[4:5], s[2:3], 0, v[0:1]
	s_add_u32 s2, s48, s7
	s_addc_u32 s3, s49, s6
	v_lshl_add_u64 v[6:7], s[2:3], 0, v[0:1]
	v_or_b32_e32 v3, 0xffffffc0, v2
	v_mov_b32_e32 v8, 0
	s_mov_b64 s[2:3], 0
	v_mov_b32_e32 v1, 0
	s_mov_b64 s[6:7], 0x100
	global_load_dword v9, v[6:7], off
	global_load_dword v10, v[4:5], off
	v_mov_b32_e32 v11, 0
	v_mov_b32_e32 v12, 0
	v_cmp_gt_u32_e32 vcc, 32, v2
	s_and_saveexec_b64 s[2:3], vcc
	global_load_dword v11, v[6:7], off offset:256
	global_load_dword v12, v[4:5], off offset:256
	s_or_b64 exec, exec, s[2:3]
	s_waitcnt vmcnt(0)
	v_max_f32_e64 v9, |v9|, |v9|
	v_max_f32_e32 v8, v8, v9
	v_max_f32_e64 v11, |v11|, |v11|
	v_max_f32_e32 v8, v8, v11
	v_max_f32_e64 v10, |v10|, |v10|
	v_max_f32_e32 v1, v1, v10
	v_max_f32_e64 v12, |v12|, |v12|
	v_max_f32_e32 v1, v1, v12
	s_or_b64 exec, exec, s[2:3]
	s_load_dwordx4 s[44:47], s[84:85], 0xa0
	s_load_dwordx2 s[10:11], s[84:85], 0xb0
	v_readlane_b32 s2, v254, 62
	v_sub_u32_e32 v3, 0xe87, v2
	v_lshrrev_b32_e32 v3, 6, v3
	v_or_b32_e32 v112, s2, v2
	v_lshlrev_b64 v[4:5], 2, v[112:113]
	s_waitcnt lgkmcnt(0)
	v_lshl_add_u64 v[6:7], s[44:45], 0, v[4:5]
	v_lshl_add_u64 v[4:5], s[46:47], 0, v[4:5]
	global_load_dword v7, v[6:7], off
	v_add_u32_e32 v10, 1, v3
	global_load_dword v6, v[4:5], off
	v_or_b32_e32 v3, 64, v2
	v_readlane_b32 s3, v254, 63
	s_mov_b32 s12, 2
	v_and_b32_e32 v9, 62, v10
	v_mov_b32_e32 v12, 0
	s_mov_b64 s[8:9], 0
	v_mov_b64_e32 v[4:5], v[2:3]
	v_mov_b32_e32 v3, 0
	v_readlane_b32 s13, v255, 10
	v_readlane_b32 s14, v255, 11
	s_nop 1
	v_add_u32_e32 v112, s13, v2
	v_lshl_add_u64 v[12:13], v[112:113], 2, s[10:11]
	s_mov_b64 s[98:99], 0x1000
	v_mov_b32_e32 v4, 0
	global_load_dword v16, v[12:13], off
	global_load_dword v17, v[12:13], off offset:256
	global_load_dword v18, v[12:13], off offset:512
	global_load_dword v19, v[12:13], off offset:768
	global_load_dword v20, v[12:13], off offset:1024
	global_load_dword v21, v[12:13], off offset:1280
	global_load_dword v22, v[12:13], off offset:1536
	global_load_dword v23, v[12:13], off offset:1792
	global_load_dword v24, v[12:13], off offset:2048
	global_load_dword v25, v[12:13], off offset:2304
	global_load_dword v26, v[12:13], off offset:2560
	global_load_dword v27, v[12:13], off offset:2816
	global_load_dword v28, v[12:13], off offset:3072
	global_load_dword v29, v[12:13], off offset:3328
	global_load_dword v30, v[12:13], off offset:3584
	global_load_dword v31, v[12:13], off offset:3840
	v_lshl_add_u64 v[12:13], v[12:13], 0, s[98:99]
	global_load_dword v32, v[12:13], off
	global_load_dword v33, v[12:13], off offset:256
	global_load_dword v34, v[12:13], off offset:512
	global_load_dword v35, v[12:13], off offset:768
	global_load_dword v36, v[12:13], off offset:1024
	global_load_dword v37, v[12:13], off offset:1280
	global_load_dword v38, v[12:13], off offset:1536
	global_load_dword v39, v[12:13], off offset:1792
	global_load_dword v40, v[12:13], off offset:2048
	global_load_dword v41, v[12:13], off offset:2304
	global_load_dword v42, v[12:13], off offset:2560
	global_load_dword v43, v[12:13], off offset:2816
	global_load_dword v44, v[12:13], off offset:3072
	global_load_dword v45, v[12:13], off offset:3328
	global_load_dword v46, v[12:13], off offset:3584
	global_load_dword v47, v[12:13], off offset:3840
	v_lshl_add_u64 v[12:13], v[12:13], 0, s[98:99]
	global_load_dword v48, v[12:13], off
	global_load_dword v49, v[12:13], off offset:256
	global_load_dword v50, v[12:13], off offset:512
	global_load_dword v51, v[12:13], off offset:768
	global_load_dword v52, v[12:13], off offset:1024
	global_load_dword v53, v[12:13], off offset:1280
	global_load_dword v54, v[12:13], off offset:1536
	global_load_dword v55, v[12:13], off offset:1792
	global_load_dword v56, v[12:13], off offset:2048
	global_load_dword v57, v[12:13], off offset:2304
	global_load_dword v58, v[12:13], off offset:2560
	global_load_dword v59, v[12:13], off offset:2816
	global_load_dword v60, v[12:13], off offset:3072
	global_load_dword v61, v[12:13], off offset:3328
	global_load_dword v62, v[12:13], off offset:3584
	global_load_dword v63, v[12:13], off offset:3840
	v_lshl_add_u64 v[12:13], v[12:13], 0, s[98:99]
	global_load_dword v64, v[12:13], off
	global_load_dword v65, v[12:13], off offset:256
	global_load_dword v66, v[12:13], off offset:512
	global_load_dword v67, v[12:13], off offset:768
	global_load_dword v68, v[12:13], off offset:1024
	global_load_dword v69, v[12:13], off offset:1280
	global_load_dword v70, v[12:13], off offset:1536
	global_load_dword v71, v[12:13], off offset:1792
	global_load_dword v72, v[12:13], off offset:2048
	global_load_dword v73, v[12:13], off offset:2304
	v_mov_b32_e32 v74, 0
	v_cmp_gt_u32_e32 vcc, 8, v2
	s_and_saveexec_b64 s[6:7], vcc
	global_load_dword v74, v[12:13], off offset:2560
	s_or_b64 exec, exec, s[6:7]
	s_waitcnt vmcnt(0)
	v_max_f32_e64 v16, |v16|, |v16|
	v_max_f32_e32 v4, v4, v16
	v_max_f32_e64 v17, |v17|, |v17|
	v_max_f32_e32 v4, v4, v17
	v_max_f32_e64 v18, |v18|, |v18|
	v_max_f32_e32 v4, v4, v18
	v_max_f32_e64 v19, |v19|, |v19|
	v_max_f32_e32 v4, v4, v19
	v_max_f32_e64 v20, |v20|, |v20|
	v_max_f32_e32 v4, v4, v20
	v_max_f32_e64 v21, |v21|, |v21|
	v_max_f32_e32 v4, v4, v21
	v_max_f32_e64 v22, |v22|, |v22|
	v_max_f32_e32 v4, v4, v22
	v_max_f32_e64 v23, |v23|, |v23|
	v_max_f32_e32 v4, v4, v23
	v_max_f32_e64 v24, |v24|, |v24|
	v_max_f32_e32 v4, v4, v24
	v_max_f32_e64 v25, |v25|, |v25|
	v_max_f32_e32 v4, v4, v25
	v_max_f32_e64 v26, |v26|, |v26|
	v_max_f32_e32 v4, v4, v26
	v_max_f32_e64 v27, |v27|, |v27|
	v_max_f32_e32 v4, v4, v27
	v_max_f32_e64 v28, |v28|, |v28|
	v_max_f32_e32 v4, v4, v28
	v_max_f32_e64 v29, |v29|, |v29|
	v_max_f32_e32 v4, v4, v29
	v_max_f32_e64 v30, |v30|, |v30|
	v_max_f32_e32 v4, v4, v30
	v_max_f32_e64 v31, |v31|, |v31|
	v_max_f32_e32 v4, v4, v31
	v_max_f32_e64 v32, |v32|, |v32|
	v_max_f32_e32 v4, v4, v32
	v_max_f32_e64 v33, |v33|, |v33|
	v_max_f32_e32 v4, v4, v33
	v_max_f32_e64 v34, |v34|, |v34|
	v_max_f32_e32 v4, v4, v34
	v_max_f32_e64 v35, |v35|, |v35|
	v_max_f32_e32 v4, v4, v35
	v_max_f32_e64 v36, |v36|, |v36|
	v_max_f32_e32 v4, v4, v36
	v_max_f32_e64 v37, |v37|, |v37|
	v_max_f32_e32 v4, v4, v37
	v_max_f32_e64 v38, |v38|, |v38|
	v_max_f32_e32 v4, v4, v38
	v_max_f32_e64 v39, |v39|, |v39|
	v_max_f32_e32 v4, v4, v39
	v_max_f32_e64 v40, |v40|, |v40|
	v_max_f32_e32 v4, v4, v40
	v_max_f32_e64 v41, |v41|, |v41|
	v_max_f32_e32 v4, v4, v41
	v_max_f32_e64 v42, |v42|, |v42|
	v_max_f32_e32 v4, v4, v42
	v_max_f32_e64 v43, |v43|, |v43|
	v_max_f32_e32 v4, v4, v43
	v_max_f32_e64 v44, |v44|, |v44|
	v_max_f32_e32 v4, v4, v44
	v_max_f32_e64 v45, |v45|, |v45|
	v_max_f32_e32 v4, v4, v45
	v_max_f32_e64 v46, |v46|, |v46|
	v_max_f32_e32 v4, v4, v46
	v_max_f32_e64 v47, |v47|, |v47|
	v_max_f32_e32 v4, v4, v47
	v_max_f32_e64 v48, |v48|, |v48|
	v_max_f32_e32 v4, v4, v48
	v_max_f32_e64 v49, |v49|, |v49|
	v_max_f32_e32 v4, v4, v49
	v_max_f32_e64 v50, |v50|, |v50|
	v_max_f32_e32 v4, v4, v50
	v_max_f32_e64 v51, |v51|, |v51|
	v_max_f32_e32 v4, v4, v51
	v_max_f32_e64 v52, |v52|, |v52|
	v_max_f32_e32 v4, v4, v52
	v_max_f32_e64 v53, |v53|, |v53|
	v_max_f32_e32 v4, v4, v53
	v_max_f32_e64 v54, |v54|, |v54|
	v_max_f32_e32 v4, v4, v54
	v_max_f32_e64 v55, |v55|, |v55|
	v_max_f32_e32 v4, v4, v55
	v_max_f32_e64 v56, |v56|, |v56|
	v_max_f32_e32 v4, v4, v56
	v_max_f32_e64 v57, |v57|, |v57|
	v_max_f32_e32 v4, v4, v57
	v_max_f32_e64 v58, |v58|, |v58|
	v_max_f32_e32 v4, v4, v58
	v_max_f32_e64 v59, |v59|, |v59|
	v_max_f32_e32 v4, v4, v59
	v_max_f32_e64 v60, |v60|, |v60|
	v_max_f32_e32 v4, v4, v60
	v_max_f32_e64 v61, |v61|, |v61|
	v_max_f32_e32 v4, v4, v61
	v_max_f32_e64 v62, |v62|, |v62|
	v_max_f32_e32 v4, v4, v62
	v_max_f32_e64 v63, |v63|, |v63|
	v_max_f32_e32 v4, v4, v63
	v_max_f32_e64 v64, |v64|, |v64|
	v_max_f32_e32 v4, v4, v64
	v_max_f32_e64 v65, |v65|, |v65|
	v_max_f32_e32 v4, v4, v65
	v_max_f32_e64 v66, |v66|, |v66|
	v_max_f32_e32 v4, v4, v66
	v_max_f32_e64 v67, |v67|, |v67|
	v_max_f32_e32 v4, v4, v67
	v_max_f32_e64 v68, |v68|, |v68|
	v_max_f32_e32 v4, v4, v68
	v_max_f32_e64 v69, |v69|, |v69|
	v_max_f32_e32 v4, v4, v69
	v_max_f32_e64 v70, |v70|, |v70|
	v_max_f32_e32 v4, v4, v70
	v_max_f32_e64 v71, |v71|, |v71|
	v_max_f32_e32 v4, v4, v71
	v_max_f32_e64 v72, |v72|, |v72|
	v_max_f32_e32 v4, v4, v72
	v_max_f32_e64 v73, |v73|, |v73|
	v_max_f32_e32 v4, v4, v73
	v_max_f32_e64 v74, |v74|, |v74|
	v_max_f32_e32 v4, v4, v74
